# S5 scan loops (both passes, both directions) by hand: ds_read_u16_d16_hi gives the f32 directly (no shift), fixed (im,re) state layout with two packed FMAs per step, one v_cvt_pk + b16/b16_d16_hi stor
# speedup vs baseline: 1.0344x; 1.0085x over previous
.LBB0_1021:
	v_add_u32_e32 v57, s57, v169
	ds_read_u16_d16_hi v58, v57 offset:128
	ds_read_u16_d16_hi v59, v57 offset:0
	ds_read_u16_d16_hi v68, v57 offset:400
	ds_read_u16_d16_hi v69, v57 offset:272
	ds_read_u16_d16_hi v70, v57 offset:672
	ds_read_u16_d16_hi v71, v57 offset:544
	ds_read_u16_d16_hi v72, v57 offset:944
	ds_read_u16_d16_hi v73, v57 offset:816
	ds_read_u16_d16_hi v74, v57 offset:1216
	ds_read_u16_d16_hi v75, v57 offset:1088
	ds_read_u16_d16_hi v76, v57 offset:1488
	ds_read_u16_d16_hi v77, v57 offset:1360
	ds_read_u16_d16_hi v78, v57 offset:1760
	ds_read_u16_d16_hi v79, v57 offset:1632
	ds_read_u16_d16_hi v80, v57 offset:2032
	ds_read_u16_d16_hi v81, v57 offset:1904
	ds_read_u16_d16_hi v82, v57 offset:2304
	ds_read_u16_d16_hi v83, v57 offset:2176
	ds_read_u16_d16_hi v84, v57 offset:2576
	ds_read_u16_d16_hi v85, v57 offset:2448
	ds_read_u16_d16_hi v86, v57 offset:2848
	ds_read_u16_d16_hi v87, v57 offset:2720
	ds_read_u16_d16_hi v88, v57 offset:3120
	ds_read_u16_d16_hi v89, v57 offset:2992
	ds_read_u16_d16_hi v90, v57 offset:3392
	ds_read_u16_d16_hi v91, v57 offset:3264
	ds_read_u16_d16_hi v92, v57 offset:3664
	ds_read_u16_d16_hi v93, v57 offset:3536
	ds_read_u16_d16_hi v94, v57 offset:3936
	ds_read_u16_d16_hi v95, v57 offset:3808
	ds_read_u16_d16_hi v96, v57 offset:4208
	ds_read_u16_d16_hi v97, v57 offset:4080
	s_waitcnt lgkmcnt(15)
	v_pk_fma_f32 v[58:59], v[50:51], v[62:63], v[58:59]
	v_pk_fma_f32 v[62:63], v[48:49], v[62:63], v[58:59] op_sel:[0,1,0] op_sel_hi:[1,0,1]
	s_waitcnt lgkmcnt(15)
	v_pk_fma_f32 v[68:69], v[50:51], v[62:63], v[68:69]
	v_pk_fma_f32 v[62:63], v[48:49], v[62:63], v[68:69] op_sel:[0,1,0] op_sel_hi:[1,0,1]
	s_waitcnt lgkmcnt(15)
	v_pk_fma_f32 v[70:71], v[50:51], v[62:63], v[70:71]
	v_pk_fma_f32 v[62:63], v[48:49], v[62:63], v[70:71] op_sel:[0,1,0] op_sel_hi:[1,0,1]
	s_waitcnt lgkmcnt(15)
	v_pk_fma_f32 v[72:73], v[50:51], v[62:63], v[72:73]
	v_pk_fma_f32 v[62:63], v[48:49], v[62:63], v[72:73] op_sel:[0,1,0] op_sel_hi:[1,0,1]
	s_waitcnt lgkmcnt(15)
	v_pk_fma_f32 v[74:75], v[50:51], v[62:63], v[74:75]
	v_pk_fma_f32 v[62:63], v[48:49], v[62:63], v[74:75] op_sel:[0,1,0] op_sel_hi:[1,0,1]
	s_waitcnt lgkmcnt(15)
	v_pk_fma_f32 v[76:77], v[50:51], v[62:63], v[76:77]
	v_pk_fma_f32 v[62:63], v[48:49], v[62:63], v[76:77] op_sel:[0,1,0] op_sel_hi:[1,0,1]
	s_waitcnt lgkmcnt(15)
	v_pk_fma_f32 v[78:79], v[50:51], v[62:63], v[78:79]
	v_pk_fma_f32 v[62:63], v[48:49], v[62:63], v[78:79] op_sel:[0,1,0] op_sel_hi:[1,0,1]
	s_waitcnt lgkmcnt(15)
	v_pk_fma_f32 v[80:81], v[50:51], v[62:63], v[80:81]
	v_pk_fma_f32 v[62:63], v[48:49], v[62:63], v[80:81] op_sel:[0,1,0] op_sel_hi:[1,0,1]
	s_waitcnt lgkmcnt(14)
	v_pk_fma_f32 v[82:83], v[50:51], v[62:63], v[82:83]
	v_pk_fma_f32 v[62:63], v[48:49], v[62:63], v[82:83] op_sel:[0,1,0] op_sel_hi:[1,0,1]
	s_waitcnt lgkmcnt(12)
	v_pk_fma_f32 v[84:85], v[50:51], v[62:63], v[84:85]
	v_pk_fma_f32 v[62:63], v[48:49], v[62:63], v[84:85] op_sel:[0,1,0] op_sel_hi:[1,0,1]
	s_waitcnt lgkmcnt(10)
	v_pk_fma_f32 v[86:87], v[50:51], v[62:63], v[86:87]
	v_pk_fma_f32 v[62:63], v[48:49], v[62:63], v[86:87] op_sel:[0,1,0] op_sel_hi:[1,0,1]
	s_waitcnt lgkmcnt(8)
	v_pk_fma_f32 v[88:89], v[50:51], v[62:63], v[88:89]
	v_pk_fma_f32 v[62:63], v[48:49], v[62:63], v[88:89] op_sel:[0,1,0] op_sel_hi:[1,0,1]
	s_waitcnt lgkmcnt(6)
	v_pk_fma_f32 v[90:91], v[50:51], v[62:63], v[90:91]
	v_pk_fma_f32 v[62:63], v[48:49], v[62:63], v[90:91] op_sel:[0,1,0] op_sel_hi:[1,0,1]
	s_waitcnt lgkmcnt(4)
	v_pk_fma_f32 v[92:93], v[50:51], v[62:63], v[92:93]
	v_pk_fma_f32 v[62:63], v[48:49], v[62:63], v[92:93] op_sel:[0,1,0] op_sel_hi:[1,0,1]
	s_waitcnt lgkmcnt(2)
	v_pk_fma_f32 v[94:95], v[50:51], v[62:63], v[94:95]
	v_pk_fma_f32 v[62:63], v[48:49], v[62:63], v[94:95] op_sel:[0,1,0] op_sel_hi:[1,0,1]
	s_waitcnt lgkmcnt(0)
	v_pk_fma_f32 v[96:97], v[50:51], v[62:63], v[96:97]
	v_pk_fma_f32 v[62:63], v[48:49], v[62:63], v[96:97] op_sel:[0,1,0] op_sel_hi:[1,0,1]
	s_addk_i32 s57, 0x1100
	s_cmpk_eq_i32 s57, 0x4400
	s_cbranch_scc0 .LBB0_1021
	s_lshl_b32 s8, s56, 8
	s_lshl_b32 s33, s37, 7
	s_or_b32 s8, s33, s8
	s_waitcnt vmcnt(7)
	v_mfma_f32_16x16x32_bf16 v[50:53], v[44:47], v[12:15], 0
	v_or_b32_e32 v48, s8, v167
	v_mov_b32_e32 v49, v145
	v_lshl_add_u64 v[54:55], v[48:49], 2, s[30:31]
	s_waitcnt vmcnt(6)
	v_mfma_f32_16x16x32_bf16 v[68:71], v[40:43], v[12:15], 0
	v_lshl_add_u64 v[48:49], v[54:55], 0, s[22:23]
	v_add_co_u32_e32 v54, vcc, 0xb79c000, v54
	s_waitcnt vmcnt(5)
	v_mfma_f32_16x16x32_bf16 v[72:75], v[36:39], v[12:15], 0
	v_pk_mov_b32 v[58:59], v[62:63], v[62:63] op_sel:[1,0]
	v_addc_co_u32_e32 v55, vcc, 0, v55, vcc
	s_waitcnt vmcnt(4)
	v_mfma_f32_16x16x32_bf16 v[76:79], v[32:35], v[12:15], 0
	global_store_dwordx2 v[54:55], v[58:59], off
	v_cvt_pk_bf16_f32 v54, v50, v51
	v_cvt_pk_bf16_f32 v55, v52, v53
	s_waitcnt vmcnt(4)
	v_mfma_f32_16x16x32_bf16 v[62:65], v[28:31], v[12:15], 0
	v_cvt_pk_bf16_f32 v58, v68, v69
	v_cvt_pk_bf16_f32 v59, v70, v71
	s_waitcnt lgkmcnt(0)
	s_waitcnt vmcnt(3)
	v_mfma_f32_16x16x32_bf16 v[80:83], v[24:27], v[12:15], 0
	ds_write2_b64 v179, v[54:55], v[58:59] offset1:4
	v_cvt_pk_bf16_f32 v54, v72, v73
	v_cvt_pk_bf16_f32 v55, v74, v75
	s_waitcnt vmcnt(2)
	v_mfma_f32_16x16x32_bf16 v[50:53], v[20:23], v[12:15], 0
	v_cvt_pk_bf16_f32 v58, v76, v77
	v_cvt_pk_bf16_f32 v59, v78, v79
	ds_write2_b64 v179, v[54:55], v[58:59] offset0:8 offset1:12
	s_waitcnt vmcnt(1)
	v_mfma_f32_16x16x32_bf16 v[12:15], v[16:19], v[12:15], 0
	v_cvt_pk_bf16_f32 v54, v62, v63
	v_cvt_pk_bf16_f32 v55, v64, v65
	v_cvt_pk_bf16_f32 v58, v80, v81
	v_mfma_f32_16x16x32_bf16 v[68:71], v[44:47], v[4:7], 0
	v_cvt_pk_bf16_f32 v59, v82, v83
	ds_write2_b64 v179, v[54:55], v[58:59] offset0:16 offset1:20
	v_cvt_pk_bf16_f32 v54, v50, v51
	v_mfma_f32_16x16x32_bf16 v[72:75], v[40:43], v[4:7], 0
	v_cvt_pk_bf16_f32 v55, v52, v53
	v_cvt_pk_bf16_f32 v12, v12, v13
	v_cvt_pk_bf16_f32 v13, v14, v15
	v_mfma_f32_16x16x32_bf16 v[62:65], v[36:39], v[4:7], 0
	ds_write2_b64 v179, v[54:55], v[12:13] offset0:24 offset1:28
	v_cvt_pk_bf16_f32 v54, v68, v69
	v_cvt_pk_bf16_f32 v55, v70, v71
	v_mfma_f32_16x16x32_bf16 v[50:53], v[32:35], v[4:7], 0
	v_cvt_pk_bf16_f32 v58, v72, v73
	v_cvt_pk_bf16_f32 v59, v74, v75
	ds_write2_b64 v66, v[54:55], v[58:59] offset0:32 offset1:36
	v_mfma_f32_16x16x32_bf16 v[12:15], v[28:31], v[4:7], 0
	v_cvt_pk_bf16_f32 v54, v62, v63
	v_cvt_pk_bf16_f32 v55, v64, v65
	s_nop 1
	v_cvt_pk_bf16_f32 v50, v50, v51
	v_mfma_f32_16x16x32_bf16 v[68:71], v[24:27], v[4:7], 0
	v_cvt_pk_bf16_f32 v51, v52, v53
	ds_write2_b64 v66, v[54:55], v[50:51] offset0:40 offset1:44
	v_cvt_pk_bf16_f32 v50, v12, v13
	v_mfma_f32_16x16x32_bf16 v[72:75], v[20:23], v[4:7], 0
	v_cvt_pk_bf16_f32 v51, v14, v15
	s_nop 2
	v_cvt_pk_bf16_f32 v52, v68, v69
	v_cvt_pk_bf16_f32 v53, v70, v71
	v_mfma_f32_16x16x32_bf16 v[4:7], v[16:19], v[4:7], 0
	ds_write2_b64 v66, v[50:51], v[52:53] offset0:48 offset1:52
	v_cvt_pk_bf16_f32 v54, v72, v73
	v_cvt_pk_bf16_f32 v55, v74, v75
	v_mfma_f32_16x16x32_bf16 v[12:15], v[44:47], v[8:11], 0
	s_movk_i32 s8, 0x3300
	s_nop 2
	v_cvt_pk_bf16_f32 v4, v4, v5
	v_cvt_pk_bf16_f32 v5, v6, v7
	v_mfma_f32_16x16x32_bf16 v[50:53], v[40:43], v[8:11], 0
	ds_write2_b64 v66, v[54:55], v[4:5] offset0:56 offset1:60
	v_cvt_pk_bf16_f32 v54, v12, v13
	v_cvt_pk_bf16_f32 v55, v14, v15
	v_mfma_f32_16x16x32_bf16 v[62:65], v[36:39], v[8:11], 0
	v_mfma_f32_16x16x32_bf16 v[4:7], v[32:35], v[8:11], 0
	s_nop 2
	v_cvt_pk_bf16_f32 v50, v50, v51
	v_cvt_pk_bf16_f32 v51, v52, v53
	ds_write2_b64 v67, v[54:55], v[50:51] offset0:64 offset1:68
	v_mfma_f32_16x16x32_bf16 v[12:15], v[28:31], v[8:11], 0
	v_cvt_pk_bf16_f32 v54, v62, v63
	v_cvt_pk_bf16_f32 v55, v64, v65
	v_cvt_pk_bf16_f32 v4, v4, v5
	v_mfma_f32_16x16x32_bf16 v[50:53], v[24:27], v[8:11], 0
	v_cvt_pk_bf16_f32 v5, v6, v7
	ds_write2_b64 v67, v[54:55], v[4:5] offset0:72 offset1:76
	s_nop 1
	v_cvt_pk_bf16_f32 v12, v12, v13
	v_mfma_f32_16x16x32_bf16 v[4:7], v[20:23], v[8:11], 0
	v_cvt_pk_bf16_f32 v13, v14, v15
	s_nop 0
	v_cvt_pk_bf16_f32 v14, v50, v51
	v_cvt_pk_bf16_f32 v15, v52, v53
	v_mfma_f32_16x16x32_bf16 v[8:11], v[16:19], v[8:11], 0
	ds_write2_b64 v67, v[12:13], v[14:15] offset0:80 offset1:84
	s_nop 1
	v_cvt_pk_bf16_f32 v50, v4, v5
	v_cvt_pk_bf16_f32 v51, v6, v7
	v_mfma_f32_16x16x32_bf16 v[12:15], v[44:47], v[0:3], 0
	v_mfma_f32_16x16x32_bf16 v[4:7], v[40:43], v[0:3], 0
	s_nop 0
	v_cvt_pk_bf16_f32 v8, v8, v9
	v_cvt_pk_bf16_f32 v9, v10, v11
	s_nop 3
	v_cvt_pk_bf16_f32 v12, v12, v13
	v_cvt_pk_bf16_f32 v13, v14, v15
	ds_write2_b64 v67, v[50:51], v[8:9] offset0:88 offset1:92
	v_cvt_pk_bf16_f32 v4, v4, v5
	v_cvt_pk_bf16_f32 v5, v6, v7
	v_mfma_f32_16x16x32_bf16 v[8:11], v[36:39], v[0:3], 0
	ds_write2_b64 v56, v[12:13], v[4:5] offset0:96 offset1:100
	v_mfma_f32_16x16x32_bf16 v[4:7], v[32:35], v[0:3], 0
	s_nop 5
	v_cvt_pk_bf16_f32 v12, v8, v9
	v_cvt_pk_bf16_f32 v13, v10, v11
	v_cvt_pk_bf16_f32 v4, v4, v5
	v_cvt_pk_bf16_f32 v5, v6, v7
	v_mfma_f32_16x16x32_bf16 v[8:11], v[28:31], v[0:3], 0
	ds_write2_b64 v56, v[12:13], v[4:5] offset0:104 offset1:108
	v_mfma_f32_16x16x32_bf16 v[4:7], v[24:27], v[0:3], 0
	s_nop 5
	v_cvt_pk_bf16_f32 v8, v8, v9
	v_cvt_pk_bf16_f32 v9, v10, v11
	v_cvt_pk_bf16_f32 v10, v4, v5
	v_cvt_pk_bf16_f32 v11, v6, v7
	v_mfma_f32_16x16x32_bf16 v[4:7], v[20:23], v[0:3], 0
	ds_write2_b64 v56, v[8:9], v[10:11] offset0:112 offset1:116
	v_mov_b32_e32 v8, 0
	v_mov_b32_e32 v9, v8
	v_mfma_f32_16x16x32_bf16 v[0:3], v[16:19], v[0:3], 0
	s_nop 3
	v_cvt_pk_bf16_f32 v4, v4, v5
	v_cvt_pk_bf16_f32 v5, v6, v7
	s_nop 1
	v_cvt_pk_bf16_f32 v0, v0, v1
	v_cvt_pk_bf16_f32 v1, v2, v3
	ds_write2_b64 v56, v[4:5], v[0:1] offset0:120 offset1:124
	s_waitcnt lgkmcnt(0)
	v_xor_b32_e32 v1, 0x80000000, v61
	v_mov_b32_e32 v0, v61
	v_mov_b32_e32 v2, v60
	v_mov_b32_e32 v3, v60
	v_mov_b32_e32 v60, v1
	v_pk_mov_b32 v[4:5], v[0:1], v[0:1] op_sel:[1,0]
	v_pk_mov_b32 v[6:7], v[60:61], v[60:61] op_sel:[1,0]
.LBB0_1023:
	v_add_u32_e32 v10, s8, v169
	ds_read_u16_d16_hi v12, v10 offset:4208
	ds_read_u16_d16_hi v13, v10 offset:4080
	ds_read_u16_d16_hi v14, v10 offset:3936
	ds_read_u16_d16_hi v15, v10 offset:3808
	ds_read_u16_d16_hi v16, v10 offset:3664
	ds_read_u16_d16_hi v17, v10 offset:3536
	ds_read_u16_d16_hi v18, v10 offset:3392
	ds_read_u16_d16_hi v19, v10 offset:3264
	ds_read_u16_d16_hi v20, v10 offset:3120
	ds_read_u16_d16_hi v21, v10 offset:2992
	ds_read_u16_d16_hi v22, v10 offset:2848
	ds_read_u16_d16_hi v23, v10 offset:2720
	ds_read_u16_d16_hi v24, v10 offset:2576
	ds_read_u16_d16_hi v25, v10 offset:2448
	ds_read_u16_d16_hi v26, v10 offset:2304
	ds_read_u16_d16_hi v27, v10 offset:2176
	ds_read_u16_d16_hi v28, v10 offset:2032
	ds_read_u16_d16_hi v29, v10 offset:1904
	ds_read_u16_d16_hi v30, v10 offset:1760
	ds_read_u16_d16_hi v31, v10 offset:1632
	ds_read_u16_d16_hi v32, v10 offset:1488
	ds_read_u16_d16_hi v33, v10 offset:1360
	ds_read_u16_d16_hi v34, v10 offset:1216
	ds_read_u16_d16_hi v35, v10 offset:1088
	ds_read_u16_d16_hi v36, v10 offset:944
	ds_read_u16_d16_hi v37, v10 offset:816
	ds_read_u16_d16_hi v38, v10 offset:672
	ds_read_u16_d16_hi v39, v10 offset:544
	ds_read_u16_d16_hi v40, v10 offset:400
	ds_read_u16_d16_hi v41, v10 offset:272
	ds_read_u16_d16_hi v11, v10 offset:0
	ds_read_u16_d16_hi v10, v10 offset:128
	s_waitcnt lgkmcnt(15)
	v_pk_fma_f32 v[12:13], v[2:3], v[8:9], v[12:13]
	v_pk_fma_f32 v[8:9], v[0:1], v[8:9], v[12:13] op_sel:[0,1,0] op_sel_hi:[1,0,1]
	s_waitcnt lgkmcnt(15)
	v_pk_fma_f32 v[14:15], v[2:3], v[8:9], v[14:15]
	v_pk_fma_f32 v[8:9], v[0:1], v[8:9], v[14:15] op_sel:[0,1,0] op_sel_hi:[1,0,1]
	s_waitcnt lgkmcnt(15)
	v_pk_fma_f32 v[16:17], v[2:3], v[8:9], v[16:17]
	v_pk_fma_f32 v[8:9], v[0:1], v[8:9], v[16:17] op_sel:[0,1,0] op_sel_hi:[1,0,1]
	s_waitcnt lgkmcnt(15)
	v_pk_fma_f32 v[18:19], v[2:3], v[8:9], v[18:19]
	v_pk_fma_f32 v[8:9], v[0:1], v[8:9], v[18:19] op_sel:[0,1,0] op_sel_hi:[1,0,1]
	s_waitcnt lgkmcnt(15)
	v_pk_fma_f32 v[20:21], v[2:3], v[8:9], v[20:21]
	v_pk_fma_f32 v[8:9], v[0:1], v[8:9], v[20:21] op_sel:[0,1,0] op_sel_hi:[1,0,1]
	s_waitcnt lgkmcnt(15)
	v_pk_fma_f32 v[22:23], v[2:3], v[8:9], v[22:23]
	v_pk_fma_f32 v[8:9], v[0:1], v[8:9], v[22:23] op_sel:[0,1,0] op_sel_hi:[1,0,1]
	s_waitcnt lgkmcnt(15)
	v_pk_fma_f32 v[24:25], v[2:3], v[8:9], v[24:25]
	v_pk_fma_f32 v[8:9], v[0:1], v[8:9], v[24:25] op_sel:[0,1,0] op_sel_hi:[1,0,1]
	s_waitcnt lgkmcnt(15)
	v_pk_fma_f32 v[26:27], v[2:3], v[8:9], v[26:27]
	v_pk_fma_f32 v[8:9], v[0:1], v[8:9], v[26:27] op_sel:[0,1,0] op_sel_hi:[1,0,1]
	s_waitcnt lgkmcnt(14)
	v_pk_fma_f32 v[28:29], v[2:3], v[8:9], v[28:29]
	v_pk_fma_f32 v[8:9], v[0:1], v[8:9], v[28:29] op_sel:[0,1,0] op_sel_hi:[1,0,1]
	s_waitcnt lgkmcnt(12)
	v_pk_fma_f32 v[30:31], v[2:3], v[8:9], v[30:31]
	v_pk_fma_f32 v[8:9], v[0:1], v[8:9], v[30:31] op_sel:[0,1,0] op_sel_hi:[1,0,1]
	s_waitcnt lgkmcnt(10)
	v_pk_fma_f32 v[32:33], v[2:3], v[8:9], v[32:33]
	v_pk_fma_f32 v[8:9], v[0:1], v[8:9], v[32:33] op_sel:[0,1,0] op_sel_hi:[1,0,1]
	s_waitcnt lgkmcnt(8)
	v_pk_fma_f32 v[34:35], v[2:3], v[8:9], v[34:35]
	v_pk_fma_f32 v[8:9], v[0:1], v[8:9], v[34:35] op_sel:[0,1,0] op_sel_hi:[1,0,1]
	s_waitcnt lgkmcnt(6)
	v_pk_fma_f32 v[36:37], v[2:3], v[8:9], v[36:37]
	v_pk_fma_f32 v[8:9], v[0:1], v[8:9], v[36:37] op_sel:[0,1,0] op_sel_hi:[1,0,1]
	s_waitcnt lgkmcnt(4)
	v_pk_fma_f32 v[38:39], v[2:3], v[8:9], v[38:39]
	v_pk_fma_f32 v[8:9], v[0:1], v[8:9], v[38:39] op_sel:[0,1,0] op_sel_hi:[1,0,1]
	s_waitcnt lgkmcnt(2)
	v_pk_fma_f32 v[40:41], v[2:3], v[8:9], v[40:41]
	v_pk_fma_f32 v[8:9], v[0:1], v[8:9], v[40:41] op_sel:[0,1,0] op_sel_hi:[1,0,1]
	s_waitcnt lgkmcnt(0)
	v_pk_fma_f32 v[10:11], v[2:3], v[8:9], v[10:11]
	v_pk_fma_f32 v[8:9], v[0:1], v[8:9], v[10:11] op_sel:[0,1,0] op_sel_hi:[1,0,1]
	s_addk_i32 s8, 0xef00
	s_cmpk_eq_i32 s8, 0xef00
	s_cbranch_scc0 .LBB0_1023
	v_pk_mov_b32 v[0:1], v[8:9], v[8:9] op_sel:[1,0]
	s_mov_b64 s[30:31], 0
	global_store_dwordx2 v[48:49], v[0:1], off offset:512

.LBB0_1105:
	v_add_u32_e32 v109, s8, v123
	ds_read_u16_d16_hi v94, v109 offset:128
	ds_read_u16_d16_hi v95, v109 offset:0
	ds_read_u16_d16_hi v96, v109 offset:400
	ds_read_u16_d16_hi v97, v109 offset:272
	ds_read_u16_d16_hi v98, v109 offset:672
	ds_read_u16_d16_hi v99, v109 offset:544
	ds_read_u16_d16_hi v100, v109 offset:944
	ds_read_u16_d16_hi v101, v109 offset:816
	ds_read_u16_d16_hi v102, v109 offset:1216
	ds_read_u16_d16_hi v103, v109 offset:1088
	ds_read_u16_d16_hi v104, v109 offset:1488
	ds_read_u16_d16_hi v105, v109 offset:1360
	ds_read_u16_d16_hi v106, v109 offset:1760
	ds_read_u16_d16_hi v107, v109 offset:1632
	ds_read_u16_d16_hi v110, v109 offset:2032
	ds_read_u16_d16_hi v111, v109 offset:1904
	ds_read_u16_d16_hi v112, v109 offset:2304
	ds_read_u16_d16_hi v113, v109 offset:2176
	ds_read_u16_d16_hi v114, v109 offset:2576
	ds_read_u16_d16_hi v115, v109 offset:2448
	ds_read_u16_d16_hi v116, v109 offset:2848
	ds_read_u16_d16_hi v117, v109 offset:2720
	ds_read_u16_d16_hi v118, v109 offset:3120
	ds_read_u16_d16_hi v119, v109 offset:2992
	ds_read_u16_d16_hi v164, v109 offset:3392
	ds_read_u16_d16_hi v165, v109 offset:3264
	ds_read_u16_d16_hi v166, v109 offset:3664
	ds_read_u16_d16_hi v167, v109 offset:3536
	ds_read_u16_d16_hi v168, v109 offset:3936
	ds_read_u16_d16_hi v169, v109 offset:3808
	ds_read_u16_d16_hi v184, v109 offset:4208
	ds_read_u16_d16_hi v185, v109 offset:4080
	s_waitcnt lgkmcnt(15)
	v_pk_fma_f32 v[94:95], v[88:89], v[160:161], v[94:95]
	v_pk_fma_f32 v[160:161], v[86:87], v[160:161], v[94:95] op_sel:[0,1,0] op_sel_hi:[1,0,1]
	v_cvt_pk_bf16_f32 v120, v161, v160
	ds_write_b16 v109, v120 offset:0
	ds_write_b16_d16_hi v109, v120 offset:128
	s_waitcnt lgkmcnt(15)
	v_pk_fma_f32 v[96:97], v[88:89], v[160:161], v[96:97]
	v_pk_fma_f32 v[160:161], v[86:87], v[160:161], v[96:97] op_sel:[0,1,0] op_sel_hi:[1,0,1]
	v_cvt_pk_bf16_f32 v120, v161, v160
	ds_write_b16 v109, v120 offset:272
	ds_write_b16_d16_hi v109, v120 offset:400
	s_waitcnt lgkmcnt(15)
	v_pk_fma_f32 v[98:99], v[88:89], v[160:161], v[98:99]
	v_pk_fma_f32 v[160:161], v[86:87], v[160:161], v[98:99] op_sel:[0,1,0] op_sel_hi:[1,0,1]
	v_cvt_pk_bf16_f32 v120, v161, v160
	ds_write_b16 v109, v120 offset:544
	ds_write_b16_d16_hi v109, v120 offset:672
	s_waitcnt lgkmcnt(15)
	v_pk_fma_f32 v[100:101], v[88:89], v[160:161], v[100:101]
	v_pk_fma_f32 v[160:161], v[86:87], v[160:161], v[100:101] op_sel:[0,1,0] op_sel_hi:[1,0,1]
	v_cvt_pk_bf16_f32 v120, v161, v160
	ds_write_b16 v109, v120 offset:816
	ds_write_b16_d16_hi v109, v120 offset:944
	s_waitcnt lgkmcnt(15)
	v_pk_fma_f32 v[102:103], v[88:89], v[160:161], v[102:103]
	v_pk_fma_f32 v[160:161], v[86:87], v[160:161], v[102:103] op_sel:[0,1,0] op_sel_hi:[1,0,1]
	v_cvt_pk_bf16_f32 v120, v161, v160
	ds_write_b16 v109, v120 offset:1088
	ds_write_b16_d16_hi v109, v120 offset:1216
	s_waitcnt lgkmcnt(15)
	v_pk_fma_f32 v[104:105], v[88:89], v[160:161], v[104:105]
	v_pk_fma_f32 v[160:161], v[86:87], v[160:161], v[104:105] op_sel:[0,1,0] op_sel_hi:[1,0,1]
	v_cvt_pk_bf16_f32 v120, v161, v160
	ds_write_b16 v109, v120 offset:1360
	ds_write_b16_d16_hi v109, v120 offset:1488
	s_waitcnt lgkmcnt(15)
	v_pk_fma_f32 v[106:107], v[88:89], v[160:161], v[106:107]
	v_pk_fma_f32 v[160:161], v[86:87], v[160:161], v[106:107] op_sel:[0,1,0] op_sel_hi:[1,0,1]
	v_cvt_pk_bf16_f32 v120, v161, v160
	ds_write_b16 v109, v120 offset:1632
	ds_write_b16_d16_hi v109, v120 offset:1760
	s_waitcnt lgkmcnt(15)
	v_pk_fma_f32 v[110:111], v[88:89], v[160:161], v[110:111]
	v_pk_fma_f32 v[160:161], v[86:87], v[160:161], v[110:111] op_sel:[0,1,0] op_sel_hi:[1,0,1]
	v_cvt_pk_bf16_f32 v120, v161, v160
	ds_write_b16 v109, v120 offset:1904
	ds_write_b16_d16_hi v109, v120 offset:2032
	s_waitcnt lgkmcnt(15)
	v_pk_fma_f32 v[112:113], v[88:89], v[160:161], v[112:113]
	v_pk_fma_f32 v[160:161], v[86:87], v[160:161], v[112:113] op_sel:[0,1,0] op_sel_hi:[1,0,1]
	v_cvt_pk_bf16_f32 v120, v161, v160
	ds_write_b16 v109, v120 offset:2176
	ds_write_b16_d16_hi v109, v120 offset:2304
	s_waitcnt lgkmcnt(15)
	v_pk_fma_f32 v[114:115], v[88:89], v[160:161], v[114:115]
	v_pk_fma_f32 v[160:161], v[86:87], v[160:161], v[114:115] op_sel:[0,1,0] op_sel_hi:[1,0,1]
	v_cvt_pk_bf16_f32 v120, v161, v160
	ds_write_b16 v109, v120 offset:2448
	ds_write_b16_d16_hi v109, v120 offset:2576
	s_waitcnt lgkmcnt(15)
	v_pk_fma_f32 v[116:117], v[88:89], v[160:161], v[116:117]
	v_pk_fma_f32 v[160:161], v[86:87], v[160:161], v[116:117] op_sel:[0,1,0] op_sel_hi:[1,0,1]
	v_cvt_pk_bf16_f32 v120, v161, v160
	ds_write_b16 v109, v120 offset:2720
	ds_write_b16_d16_hi v109, v120 offset:2848
	s_waitcnt lgkmcnt(15)
	v_pk_fma_f32 v[118:119], v[88:89], v[160:161], v[118:119]
	v_pk_fma_f32 v[160:161], v[86:87], v[160:161], v[118:119] op_sel:[0,1,0] op_sel_hi:[1,0,1]
	v_cvt_pk_bf16_f32 v120, v161, v160
	ds_write_b16 v109, v120 offset:2992
	ds_write_b16_d16_hi v109, v120 offset:3120
	s_waitcnt lgkmcnt(15)
	v_pk_fma_f32 v[164:165], v[88:89], v[160:161], v[164:165]
	v_pk_fma_f32 v[160:161], v[86:87], v[160:161], v[164:165] op_sel:[0,1,0] op_sel_hi:[1,0,1]
	v_cvt_pk_bf16_f32 v120, v161, v160
	ds_write_b16 v109, v120 offset:3264
	ds_write_b16_d16_hi v109, v120 offset:3392
	s_waitcnt lgkmcnt(15)
	v_pk_fma_f32 v[166:167], v[88:89], v[160:161], v[166:167]
	v_pk_fma_f32 v[160:161], v[86:87], v[160:161], v[166:167] op_sel:[0,1,0] op_sel_hi:[1,0,1]
	v_cvt_pk_bf16_f32 v120, v161, v160
	ds_write_b16 v109, v120 offset:3536
	ds_write_b16_d16_hi v109, v120 offset:3664
	s_waitcnt lgkmcnt(15)
	v_pk_fma_f32 v[168:169], v[88:89], v[160:161], v[168:169]
	v_pk_fma_f32 v[160:161], v[86:87], v[160:161], v[168:169] op_sel:[0,1,0] op_sel_hi:[1,0,1]
	v_cvt_pk_bf16_f32 v120, v161, v160
	ds_write_b16 v109, v120 offset:3808
	ds_write_b16_d16_hi v109, v120 offset:3936
	s_waitcnt lgkmcnt(15)
	v_pk_fma_f32 v[184:185], v[88:89], v[160:161], v[184:185]
	v_pk_fma_f32 v[160:161], v[86:87], v[160:161], v[184:185] op_sel:[0,1,0] op_sel_hi:[1,0,1]
	v_cvt_pk_bf16_f32 v120, v161, v160
	ds_write_b16 v109, v120 offset:4080
	ds_write_b16_d16_hi v109, v120 offset:4208
	s_addk_i32 s8, 0x1100
	s_cmpk_eq_i32 s8, 0x4400
	s_cbranch_scc0 .LBB0_1105
	s_waitcnt lgkmcnt(0)
	ds_read_b128 v[84:87], v180
	ds_read_b128 v[88:91], v180 offset:64
	s_xor_b64 s[40:41], s[6:7], -1
	s_waitcnt vmcnt(16) lgkmcnt(1)
	v_mfma_f32_16x16x32_bf16 v[84:87], v[76:79], v[84:87], 0
	s_waitcnt vmcnt(15) lgkmcnt(0)
	v_mfma_f32_16x16x32_bf16 v[84:87], v[80:83], v[88:91], v[84:87]
	ds_read_b128 v[88:91], v180 offset:128
	ds_read_b128 v[92:95], v180 offset:192
	s_waitcnt vmcnt(14) lgkmcnt(1)
	v_mfma_f32_16x16x32_bf16 v[84:87], v[68:71], v[88:91], v[84:87]
	s_waitcnt vmcnt(13) lgkmcnt(0)
	v_mfma_f32_16x16x32_bf16 v[84:87], v[72:75], v[92:95], v[84:87]
	ds_read_b128 v[88:91], v180 offset:4352
	ds_read_b128 v[92:95], v180 offset:4416
	s_waitcnt lgkmcnt(1)
	v_mfma_f32_16x16x32_bf16 v[88:91], v[76:79], v[88:91], 0
	s_waitcnt lgkmcnt(0)
	v_mfma_f32_16x16x32_bf16 v[88:91], v[80:83], v[92:95], v[88:91]
	ds_read_b128 v[92:95], v180 offset:4480
	ds_read_b128 v[96:99], v180 offset:4544
	s_waitcnt lgkmcnt(1)
	v_mfma_f32_16x16x32_bf16 v[88:91], v[68:71], v[92:95], v[88:91]
	s_waitcnt lgkmcnt(0)
	v_mfma_f32_16x16x32_bf16 v[88:91], v[72:75], v[96:99], v[88:91]
	ds_read_b128 v[92:95], v180 offset:8704
	ds_read_b128 v[96:99], v180 offset:8768
	s_waitcnt lgkmcnt(1)
	v_mfma_f32_16x16x32_bf16 v[92:95], v[76:79], v[92:95], 0
	s_waitcnt lgkmcnt(0)
	v_mfma_f32_16x16x32_bf16 v[92:95], v[80:83], v[96:99], v[92:95]
	ds_read_b128 v[96:99], v180 offset:8832
	ds_read_b128 v[100:103], v180 offset:8896
	s_waitcnt lgkmcnt(1)
	v_mfma_f32_16x16x32_bf16 v[92:95], v[68:71], v[96:99], v[92:95]
	s_waitcnt lgkmcnt(0)
	v_mfma_f32_16x16x32_bf16 v[92:95], v[72:75], v[100:103], v[92:95]
	ds_read_b128 v[96:99], v180 offset:13056
	ds_read_b128 v[100:103], v180 offset:13120
	s_waitcnt lgkmcnt(1)
	v_mfma_f32_16x16x32_bf16 v[76:79], v[76:79], v[96:99], 0
	ds_read_b128 v[96:99], v180 offset:13184
	s_waitcnt lgkmcnt(1)
	v_mfma_f32_16x16x32_bf16 v[78:81], v[80:83], v[100:103], v[76:79]
	ds_read_b128 v[100:103], v180 offset:13248
	s_waitcnt lgkmcnt(1)
	v_mfma_f32_16x16x32_bf16 v[68:71], v[68:71], v[96:99], v[78:81]
	s_nop 1
	v_add_u32_e32 v76, -1, v181
	v_cmp_eq_u32_e32 vcc, v141, v76
	s_and_b64 s[10:11], s[40:41], vcc
	s_waitcnt lgkmcnt(0)
	v_mfma_f32_16x16x32_bf16 v[68:71], v[72:75], v[100:103], v[68:71]
	s_and_saveexec_b64 s[8:9], s[10:11]
	s_cbranch_execz .LBB0_1108
	s_load_dwordx2 s[10:11], s[52:53], 0xe0
	v_lshlrev_b64 v[72:73], 9, v[158:159]
	v_pk_mov_b32 v[74:75], v[160:161], v[160:161] op_sel:[1,0]
	s_waitcnt lgkmcnt(0)
	v_lshl_add_u64 v[72:73], s[10:11], 0, v[72:73]
	v_lshl_add_u64 v[72:73], v[72:73], 0, v[128:129]
	v_add_co_u32_e32 v72, vcc, 0x4000000, v72
	s_nop 1
	v_addc_co_u32_e32 v73, vcc, 0, v73, vcc
	global_store_dwordx2 v[72:73], v[74:75], off

.LBB0_1115:
	v_add_u32_e32 v58, s6, v123
	ds_read_u16_d16_hi v26, v58 offset:4208
	ds_read_u16_d16_hi v27, v58 offset:4080
	ds_read_u16_d16_hi v28, v58 offset:3936
	ds_read_u16_d16_hi v29, v58 offset:3808
	ds_read_u16_d16_hi v30, v58 offset:3664
	ds_read_u16_d16_hi v31, v58 offset:3536
	ds_read_u16_d16_hi v32, v58 offset:3392
	ds_read_u16_d16_hi v33, v58 offset:3264
	ds_read_u16_d16_hi v34, v58 offset:3120
	ds_read_u16_d16_hi v35, v58 offset:2992
	ds_read_u16_d16_hi v36, v58 offset:2848
	ds_read_u16_d16_hi v37, v58 offset:2720
	ds_read_u16_d16_hi v38, v58 offset:2576
	ds_read_u16_d16_hi v39, v58 offset:2448
	ds_read_u16_d16_hi v40, v58 offset:2304
	ds_read_u16_d16_hi v41, v58 offset:2176
	ds_read_u16_d16_hi v42, v58 offset:2032
	ds_read_u16_d16_hi v43, v58 offset:1904
	ds_read_u16_d16_hi v44, v58 offset:1760
	ds_read_u16_d16_hi v45, v58 offset:1632
	ds_read_u16_d16_hi v46, v58 offset:1488
	ds_read_u16_d16_hi v47, v58 offset:1360
	ds_read_u16_d16_hi v48, v58 offset:1216
	ds_read_u16_d16_hi v49, v58 offset:1088
	ds_read_u16_d16_hi v50, v58 offset:944
	ds_read_u16_d16_hi v51, v58 offset:816
	ds_read_u16_d16_hi v52, v58 offset:672
	ds_read_u16_d16_hi v53, v58 offset:544
	ds_read_u16_d16_hi v54, v58 offset:400
	ds_read_u16_d16_hi v55, v58 offset:272
	ds_read_u16_d16_hi v56, v58 offset:128
	ds_read_u16_d16_hi v57, v58 offset:0
	s_waitcnt lgkmcnt(15)
	v_pk_fma_f32 v[26:27], v[20:21], v[74:75], v[26:27]
	v_pk_fma_f32 v[74:75], v[18:19], v[74:75], v[26:27] op_sel:[0,1,0] op_sel_hi:[1,0,1]
	v_cvt_pk_bf16_f32 v59, v75, v74
	ds_write_b16 v58, v59 offset:4080
	ds_write_b16_d16_hi v58, v59 offset:4208
	s_waitcnt lgkmcnt(15)
	v_pk_fma_f32 v[28:29], v[20:21], v[74:75], v[28:29]
	v_pk_fma_f32 v[74:75], v[18:19], v[74:75], v[28:29] op_sel:[0,1,0] op_sel_hi:[1,0,1]
	v_cvt_pk_bf16_f32 v59, v75, v74
	ds_write_b16 v58, v59 offset:3808
	ds_write_b16_d16_hi v58, v59 offset:3936
	s_waitcnt lgkmcnt(15)
	v_pk_fma_f32 v[30:31], v[20:21], v[74:75], v[30:31]
	v_pk_fma_f32 v[74:75], v[18:19], v[74:75], v[30:31] op_sel:[0,1,0] op_sel_hi:[1,0,1]
	v_cvt_pk_bf16_f32 v59, v75, v74
	ds_write_b16 v58, v59 offset:3536
	ds_write_b16_d16_hi v58, v59 offset:3664
	s_waitcnt lgkmcnt(15)
	v_pk_fma_f32 v[32:33], v[20:21], v[74:75], v[32:33]
	v_pk_fma_f32 v[74:75], v[18:19], v[74:75], v[32:33] op_sel:[0,1,0] op_sel_hi:[1,0,1]
	v_cvt_pk_bf16_f32 v59, v75, v74
	ds_write_b16 v58, v59 offset:3264
	ds_write_b16_d16_hi v58, v59 offset:3392
	s_waitcnt lgkmcnt(15)
	v_pk_fma_f32 v[34:35], v[20:21], v[74:75], v[34:35]
	v_pk_fma_f32 v[74:75], v[18:19], v[74:75], v[34:35] op_sel:[0,1,0] op_sel_hi:[1,0,1]
	v_cvt_pk_bf16_f32 v59, v75, v74
	ds_write_b16 v58, v59 offset:2992
	ds_write_b16_d16_hi v58, v59 offset:3120
	s_waitcnt lgkmcnt(15)
	v_pk_fma_f32 v[36:37], v[20:21], v[74:75], v[36:37]
	v_pk_fma_f32 v[74:75], v[18:19], v[74:75], v[36:37] op_sel:[0,1,0] op_sel_hi:[1,0,1]
	v_cvt_pk_bf16_f32 v59, v75, v74
	ds_write_b16 v58, v59 offset:2720
	ds_write_b16_d16_hi v58, v59 offset:2848
	s_waitcnt lgkmcnt(15)
	v_pk_fma_f32 v[38:39], v[20:21], v[74:75], v[38:39]
	v_pk_fma_f32 v[74:75], v[18:19], v[74:75], v[38:39] op_sel:[0,1,0] op_sel_hi:[1,0,1]
	v_cvt_pk_bf16_f32 v59, v75, v74
	ds_write_b16 v58, v59 offset:2448
	ds_write_b16_d16_hi v58, v59 offset:2576
	s_waitcnt lgkmcnt(15)
	v_pk_fma_f32 v[40:41], v[20:21], v[74:75], v[40:41]
	v_pk_fma_f32 v[74:75], v[18:19], v[74:75], v[40:41] op_sel:[0,1,0] op_sel_hi:[1,0,1]
	v_cvt_pk_bf16_f32 v59, v75, v74
	ds_write_b16 v58, v59 offset:2176
	ds_write_b16_d16_hi v58, v59 offset:2304
	s_waitcnt lgkmcnt(15)
	v_pk_fma_f32 v[42:43], v[20:21], v[74:75], v[42:43]
	v_pk_fma_f32 v[74:75], v[18:19], v[74:75], v[42:43] op_sel:[0,1,0] op_sel_hi:[1,0,1]
	v_cvt_pk_bf16_f32 v59, v75, v74
	ds_write_b16 v58, v59 offset:1904
	ds_write_b16_d16_hi v58, v59 offset:2032
	s_waitcnt lgkmcnt(15)
	v_pk_fma_f32 v[44:45], v[20:21], v[74:75], v[44:45]
	v_pk_fma_f32 v[74:75], v[18:19], v[74:75], v[44:45] op_sel:[0,1,0] op_sel_hi:[1,0,1]
	v_cvt_pk_bf16_f32 v59, v75, v74
	ds_write_b16 v58, v59 offset:1632
	ds_write_b16_d16_hi v58, v59 offset:1760
	s_waitcnt lgkmcnt(15)
	v_pk_fma_f32 v[46:47], v[20:21], v[74:75], v[46:47]
	v_pk_fma_f32 v[74:75], v[18:19], v[74:75], v[46:47] op_sel:[0,1,0] op_sel_hi:[1,0,1]
	v_cvt_pk_bf16_f32 v59, v75, v74
	ds_write_b16 v58, v59 offset:1360
	ds_write_b16_d16_hi v58, v59 offset:1488
	s_waitcnt lgkmcnt(15)
	v_pk_fma_f32 v[48:49], v[20:21], v[74:75], v[48:49]
	v_pk_fma_f32 v[74:75], v[18:19], v[74:75], v[48:49] op_sel:[0,1,0] op_sel_hi:[1,0,1]
	v_cvt_pk_bf16_f32 v59, v75, v74
	ds_write_b16 v58, v59 offset:1088
	ds_write_b16_d16_hi v58, v59 offset:1216
	s_waitcnt lgkmcnt(15)
	v_pk_fma_f32 v[50:51], v[20:21], v[74:75], v[50:51]
	v_pk_fma_f32 v[74:75], v[18:19], v[74:75], v[50:51] op_sel:[0,1,0] op_sel_hi:[1,0,1]
	v_cvt_pk_bf16_f32 v59, v75, v74
	ds_write_b16 v58, v59 offset:816
	ds_write_b16_d16_hi v58, v59 offset:944
	s_waitcnt lgkmcnt(15)
	v_pk_fma_f32 v[52:53], v[20:21], v[74:75], v[52:53]
	v_pk_fma_f32 v[74:75], v[18:19], v[74:75], v[52:53] op_sel:[0,1,0] op_sel_hi:[1,0,1]
	v_cvt_pk_bf16_f32 v59, v75, v74
	ds_write_b16 v58, v59 offset:544
	ds_write_b16_d16_hi v58, v59 offset:672
	s_waitcnt lgkmcnt(15)
	v_pk_fma_f32 v[54:55], v[20:21], v[74:75], v[54:55]
	v_pk_fma_f32 v[74:75], v[18:19], v[74:75], v[54:55] op_sel:[0,1,0] op_sel_hi:[1,0,1]
	v_cvt_pk_bf16_f32 v59, v75, v74
	ds_write_b16 v58, v59 offset:272
	ds_write_b16_d16_hi v58, v59 offset:400
	s_waitcnt lgkmcnt(15)
	v_pk_fma_f32 v[56:57], v[20:21], v[74:75], v[56:57]
	v_pk_fma_f32 v[74:75], v[18:19], v[74:75], v[56:57] op_sel:[0,1,0] op_sel_hi:[1,0,1]
	v_cvt_pk_bf16_f32 v59, v75, v74
	ds_write_b16 v58, v59 offset:0
	ds_write_b16_d16_hi v58, v59 offset:128
	s_addk_i32 s6, 0xef00
	s_cmpk_lg_i32 s6, 0xef00
	s_cbranch_scc1 .LBB0_1115
	s_waitcnt lgkmcnt(0)
	ds_read_b128 v[16:19], v180
	ds_read_b128 v[20:23], v180 offset:64
	v_cmp_eq_u32_e32 vcc, 0, v141
	s_and_b64 s[8:9], s[40:41], vcc
	s_waitcnt vmcnt(3) lgkmcnt(1)
	v_mfma_f32_16x16x32_bf16 v[16:19], v[8:11], v[16:19], v[84:87]
	s_waitcnt vmcnt(2) lgkmcnt(0)
	v_mfma_f32_16x16x32_bf16 v[16:19], v[12:15], v[20:23], v[16:19]
	ds_read_b128 v[20:23], v180 offset:128
	ds_read_b128 v[24:27], v180 offset:192
	s_waitcnt vmcnt(1) lgkmcnt(1)
	v_mfma_f32_16x16x32_bf16 v[16:19], v[4:7], v[20:23], v[16:19]
	s_waitcnt vmcnt(0) lgkmcnt(0)
	v_mfma_f32_16x16x32_bf16 v[24:27], v[0:3], v[24:27], v[16:19]
	s_nop 5
	ds_read_b128 v[16:19], v180 offset:4352
	ds_read_b128 v[20:23], v180 offset:4416
	s_waitcnt lgkmcnt(1)
	v_mfma_f32_16x16x32_bf16 v[16:19], v[8:11], v[16:19], v[88:91]
	s_waitcnt lgkmcnt(0)
	v_mfma_f32_16x16x32_bf16 v[16:19], v[12:15], v[20:23], v[16:19]
	ds_read_b128 v[20:23], v180 offset:4480
	ds_read_b128 v[28:31], v180 offset:4544
	s_waitcnt lgkmcnt(1)
	v_mfma_f32_16x16x32_bf16 v[16:19], v[4:7], v[20:23], v[16:19]
	s_waitcnt lgkmcnt(0)
	v_mfma_f32_16x16x32_bf16 v[20:23], v[0:3], v[28:31], v[16:19]
	s_nop 5
	ds_read_b128 v[16:19], v180 offset:8704
	ds_read_b128 v[28:31], v180 offset:8768
	s_waitcnt lgkmcnt(1)
	v_mfma_f32_16x16x32_bf16 v[16:19], v[8:11], v[16:19], v[92:95]
	s_waitcnt lgkmcnt(0)
	v_mfma_f32_16x16x32_bf16 v[16:19], v[12:15], v[28:31], v[16:19]
	ds_read_b128 v[28:31], v180 offset:8832
	ds_read_b128 v[32:35], v180 offset:8896
	s_waitcnt lgkmcnt(1)
	v_mfma_f32_16x16x32_bf16 v[16:19], v[4:7], v[28:31], v[16:19]
	s_waitcnt lgkmcnt(0)
	v_mfma_f32_16x16x32_bf16 v[16:19], v[0:3], v[32:35], v[16:19]
	ds_read_b128 v[28:31], v180 offset:13056
	ds_read_b128 v[32:35], v180 offset:13120
	s_waitcnt lgkmcnt(1)
	v_mfma_f32_16x16x32_bf16 v[8:11], v[8:11], v[28:31], v[68:71]
	s_waitcnt lgkmcnt(0)
	v_mfma_f32_16x16x32_bf16 v[8:11], v[12:15], v[32:35], v[8:11]
	ds_read_b128 v[12:15], v180 offset:13184
	ds_read_b128 v[28:31], v180 offset:13248
	s_waitcnt lgkmcnt(1)
	v_mfma_f32_16x16x32_bf16 v[4:7], v[4:7], v[12:15], v[8:11]
	s_waitcnt lgkmcnt(0)
	v_mfma_f32_16x16x32_bf16 v[0:3], v[0:3], v[28:31], v[4:7]
	s_and_saveexec_b64 s[6:7], s[8:9]
	s_cbranch_execz .LBB0_1085
	s_load_dwordx2 s[8:9], s[52:53], 0xe0
	s_nop 2
	v_lshlrev_b64 v[4:5], 9, v[72:73]
	v_pk_mov_b32 v[6:7], v[74:75], v[74:75] op_sel:[1,0]
	s_waitcnt lgkmcnt(0)
	v_lshl_add_u64 v[4:5], s[8:9], 0, v[4:5]
	v_lshl_add_u64 v[4:5], v[4:5], 0, v[128:129]
	v_add_co_u32_e32 v4, vcc, 0x4000000, v4
	s_nop 1
	v_addc_co_u32_e32 v5, vcc, 0, v5, vcc
	global_store_dwordx2 v[4:5], v[6:7], off
	s_branch .LBB0_1085
